# combined: early P9 start + latent attention exact K/V prefetch waits + batched bias reads + mid-block setprio pairs removed
# speedup vs baseline: 1.0088x; 1.0088x over previous
.LBB0_849:
	s_cmp_gt_u32 s62, 15
	s_mov_b64 s[10:11], -1
	s_cbranch_scc0 .LBB0_979
	s_sub_i32 s10, s20, 20
	s_lshr_b32 s10, s10, 1
	s_and_b32 s11, s62, 1
	s_add_i32 s10, s10, s60
	v_lshl_or_b32 v0, s11, 5, v198
	s_mulk_i32 s10, 0x7c
	s_add_i32 s10, s15, s10
	v_sub_u32_e32 v1, v0, v193
	v_lshl_add_u32 v5, v1, 2, s10
	s_cmp_lg_u32 s11, s47
	v_sub_u32_e32 v6, v0, v223
	s_mov_b64 s[10:11], -1
	s_cbranch_scc0 .LBB0_875
	s_and_b64 vcc, exec, s[6:7]
	s_cbranch_vccz .LBB0_863
	s_waitcnt vmcnt(23)
	v_mfma_f32_32x32x16_bf16 v[48:63], v[96:99], v[80:83], 0
	v_add_u32_e32 v0, 24, v6
	v_cmp_gt_u32_e32 vcc, 16, v0
	v_mov_b32_e32 v0, 0xf149f2ca
	v_mov_b32_e32 v1, 0xf149f2ca
	s_waitcnt vmcnt(22)
	v_mfma_f32_32x32x16_bf16 v[48:63], v[100:103], v[84:87], v[48:63]
	s_waitcnt vmcnt(19)
	v_mfma_f32_32x32x16_bf16 v[48:63], v[112:115], v[88:91], v[48:63]
	s_waitcnt vmcnt(18)
	v_mfma_f32_32x32x16_bf16 v[48:63], v[116:119], v[92:95], v[48:63]
	ds_read_b32 v233, v5 offset:2048
	ds_read_b32 v234, v5 offset:2052
	ds_read_b32 v235, v5 offset:2056
	ds_read_b32 v236, v5 offset:2060
	s_waitcnt lgkmcnt(0)
	s_nop 7
	v_fmac_f32_e32 v233, 0x3e38aa3b, v60
	s_nop 0
	v_cndmask_b32_e32 v1, v1, v233, vcc
	v_add_u32_e32 v3, 25, v6
	v_cmp_gt_u32_e32 vcc, 16, v3
	v_fmac_f32_e32 v234, 0x3e38aa3b, v61
	s_nop 0
	v_cndmask_b32_e32 v0, v0, v234, vcc
	v_add_u32_e32 v3, 26, v6
	v_cmp_gt_u32_e32 vcc, 16, v3
	v_mov_b32_e32 v3, 0xf149f2ca
	v_mov_b32_e32 v7, 0xf149f2ca
	v_fmac_f32_e32 v235, 0x3e38aa3b, v62
	s_nop 0
	v_cndmask_b32_e32 v7, v7, v235, vcc
	v_add_u32_e32 v8, 27, v6
	v_cmp_gt_u32_e32 vcc, 16, v8
	v_fmac_f32_e32 v236, 0x3e38aa3b, v63
	s_nop 0
	v_cndmask_b32_e32 v3, v3, v236, vcc
	v_max_f32_e32 v8, v0, v0
	v_max_f32_e32 v9, v1, v1
	v_max_f32_e32 v8, v9, v8
	v_max3_f32 v9, v8, v7, v3
	ds_bpermute_b32 v10, v224, v9
	v_mov_b64_e32 v[78:79], v[46:47]
	v_mov_b64_e32 v[62:63], v[30:31]
	v_mov_b32_e32 v8, v201
	v_mov_b32_e32 v205, v4
	s_waitcnt lgkmcnt(0)
	v_max3_f32 v9, v4, v9, v10
	v_mov_b64_e32 v[76:77], v[44:45]
	v_mov_b64_e32 v[74:75], v[42:43]
	v_mov_b64_e32 v[72:73], v[40:41]
	v_mov_b64_e32 v[70:71], v[38:39]
	v_mov_b64_e32 v[68:69], v[36:37]
	v_mov_b64_e32 v[66:67], v[34:35]
	v_mov_b64_e32 v[64:65], v[32:33]
	v_cmp_gt_f32_e32 vcc, v9, v4
	v_mov_b64_e32 v[60:61], v[28:29]
	v_mov_b64_e32 v[58:59], v[26:27]
	v_mov_b64_e32 v[56:57], v[24:25]
	v_mov_b64_e32 v[54:55], v[22:23]
	v_mov_b64_e32 v[52:53], v[20:21]
	v_mov_b64_e32 v[50:51], v[18:19]
	v_mov_b64_e32 v[48:49], v[16:17]
	s_cbranch_vccz .LBB0_862
	v_sub_f32_e32 v8, v4, v9
	v_exp_f32_e32 v10, v8
	v_mov_b32_e32 v205, v9
	v_mul_f32_e32 v8, v201, v10
	v_pk_mul_f32 v[62:63], v[30:31], v[10:11] op_sel_hi:[1,0]
	v_pk_mul_f32 v[60:61], v[28:29], v[10:11] op_sel_hi:[1,0]
	v_pk_mul_f32 v[58:59], v[26:27], v[10:11] op_sel_hi:[1,0]
	v_pk_mul_f32 v[56:57], v[24:25], v[10:11] op_sel_hi:[1,0]
	v_pk_mul_f32 v[54:55], v[22:23], v[10:11] op_sel_hi:[1,0]
	v_pk_mul_f32 v[52:53], v[20:21], v[10:11] op_sel_hi:[1,0]
	v_pk_mul_f32 v[50:51], v[18:19], v[10:11] op_sel_hi:[1,0]
	v_pk_mul_f32 v[48:49], v[16:17], v[10:11] op_sel_hi:[1,0]
	v_pk_mul_f32 v[78:79], v[46:47], v[10:11] op_sel_hi:[1,0]
	v_pk_mul_f32 v[76:77], v[44:45], v[10:11] op_sel_hi:[1,0]
	v_pk_mul_f32 v[74:75], v[42:43], v[10:11] op_sel_hi:[1,0]
	v_pk_mul_f32 v[72:73], v[40:41], v[10:11] op_sel_hi:[1,0]
	v_pk_mul_f32 v[70:71], v[38:39], v[10:11] op_sel_hi:[1,0]
	v_pk_mul_f32 v[68:69], v[36:37], v[10:11] op_sel_hi:[1,0]
	v_pk_mul_f32 v[66:67], v[34:35], v[10:11] op_sel_hi:[1,0]
	v_pk_mul_f32 v[64:65], v[32:33], v[10:11] op_sel_hi:[1,0]

.LBB0_863:
	s_and_b64 vcc, exec, s[10:11]
	s_cbranch_vccz .LBB0_1054
	s_waitcnt vmcnt(23)
	v_mfma_f32_32x32x16_bf16 v[48:63], v[96:99], v[80:83], 0
	v_cmp_gt_u32_e32 vcc, 16, v6
	v_mov_b32_e32 v1, 0xf149f2ca
	v_mov_b32_e32 v0, 0xf149f2ca
	s_waitcnt vmcnt(22)
	v_mfma_f32_32x32x16_bf16 v[48:63], v[100:103], v[84:87], v[48:63]
	s_waitcnt vmcnt(19)
	v_mfma_f32_32x32x16_bf16 v[48:63], v[112:115], v[88:91], v[48:63]
	s_waitcnt vmcnt(18)
	v_mfma_f32_32x32x16_bf16 v[48:63], v[116:119], v[92:95], v[48:63]
	ds_read_b32 v233, v5 offset:1952
	ds_read_b32 v234, v5 offset:1956
	ds_read_b32 v235, v5 offset:1960
	ds_read_b32 v236, v5 offset:1964
	s_waitcnt lgkmcnt(0)
	s_nop 7
	v_fmac_f32_e32 v233, 0x3e38aa3b, v48
	s_nop 0
	v_cndmask_b32_e32 v0, v0, v233, vcc
	v_add_u32_e32 v3, 1, v6
	v_cmp_gt_u32_e32 vcc, 16, v3
	v_fmac_f32_e32 v234, 0x3e38aa3b, v49
	s_nop 0
	v_cndmask_b32_e32 v1, v1, v234, vcc
	v_add_u32_e32 v3, 2, v6
	v_cmp_gt_u32_e32 vcc, 16, v3
	v_mov_b32_e32 v7, 0xf149f2ca
	v_mov_b32_e32 v3, 0xf149f2ca
	v_fmac_f32_e32 v235, 0x3e38aa3b, v50
	s_nop 0
	v_cndmask_b32_e32 v3, v3, v235, vcc
	v_add_u32_e32 v8, 3, v6
	v_cmp_gt_u32_e32 vcc, 16, v8
	v_fmac_f32_e32 v236, 0x3e38aa3b, v51
	s_nop 0
	v_cndmask_b32_e32 v7, v7, v236, vcc
	v_max_f32_e32 v8, v1, v1
	v_max_f32_e32 v9, v0, v0
	v_max_f32_e32 v8, v9, v8
	v_max3_f32 v9, v8, v3, v7
	ds_bpermute_b32 v10, v224, v9
	v_mov_b64_e32 v[78:79], v[46:47]
	v_mov_b64_e32 v[62:63], v[30:31]
	v_mov_b32_e32 v8, v201
	v_mov_b32_e32 v205, v4
	s_waitcnt lgkmcnt(0)
	v_max3_f32 v9, v4, v9, v10
	v_mov_b64_e32 v[76:77], v[44:45]
	v_mov_b64_e32 v[74:75], v[42:43]
	v_mov_b64_e32 v[72:73], v[40:41]
	v_mov_b64_e32 v[70:71], v[38:39]
	v_mov_b64_e32 v[68:69], v[36:37]
	v_mov_b64_e32 v[66:67], v[34:35]
	v_mov_b64_e32 v[64:65], v[32:33]
	v_cmp_gt_f32_e32 vcc, v9, v4
	v_mov_b64_e32 v[60:61], v[28:29]
	v_mov_b64_e32 v[58:59], v[26:27]
	v_mov_b64_e32 v[56:57], v[24:25]
	v_mov_b64_e32 v[54:55], v[22:23]
	v_mov_b64_e32 v[52:53], v[20:21]
	v_mov_b64_e32 v[50:51], v[18:19]
	v_mov_b64_e32 v[48:49], v[16:17]
	s_cbranch_vccz .LBB0_874
	v_sub_f32_e32 v8, v4, v9
	v_exp_f32_e32 v10, v8
	v_mov_b32_e32 v205, v9
	v_mul_f32_e32 v8, v201, v10
	v_pk_mul_f32 v[62:63], v[30:31], v[10:11] op_sel_hi:[1,0]
	v_pk_mul_f32 v[60:61], v[28:29], v[10:11] op_sel_hi:[1,0]
	v_pk_mul_f32 v[58:59], v[26:27], v[10:11] op_sel_hi:[1,0]
	v_pk_mul_f32 v[56:57], v[24:25], v[10:11] op_sel_hi:[1,0]
	v_pk_mul_f32 v[54:55], v[22:23], v[10:11] op_sel_hi:[1,0]
	v_pk_mul_f32 v[52:53], v[20:21], v[10:11] op_sel_hi:[1,0]
	v_pk_mul_f32 v[50:51], v[18:19], v[10:11] op_sel_hi:[1,0]
	v_pk_mul_f32 v[48:49], v[16:17], v[10:11] op_sel_hi:[1,0]
	v_pk_mul_f32 v[78:79], v[46:47], v[10:11] op_sel_hi:[1,0]
	v_pk_mul_f32 v[76:77], v[44:45], v[10:11] op_sel_hi:[1,0]
	v_pk_mul_f32 v[74:75], v[42:43], v[10:11] op_sel_hi:[1,0]
	v_pk_mul_f32 v[72:73], v[40:41], v[10:11] op_sel_hi:[1,0]
	v_pk_mul_f32 v[70:71], v[38:39], v[10:11] op_sel_hi:[1,0]
	v_pk_mul_f32 v[68:69], v[36:37], v[10:11] op_sel_hi:[1,0]
	v_pk_mul_f32 v[66:67], v[34:35], v[10:11] op_sel_hi:[1,0]
	v_pk_mul_f32 v[64:65], v[32:33], v[10:11] op_sel_hi:[1,0]

.LBB0_876:
	s_waitcnt vmcnt(23)
	v_mfma_f32_32x32x16_bf16 v[48:63], v[96:99], v[80:83], 0
	v_cmp_gt_u32_e32 vcc, 16, v6
	v_mov_b32_e32 v0, 0xf149f2ca
	v_mov_b32_e32 v1, 0xf149f2ca
	s_waitcnt vmcnt(22)
	v_mfma_f32_32x32x16_bf16 v[48:63], v[100:103], v[84:87], v[48:63]
	s_waitcnt vmcnt(19)
	v_mfma_f32_32x32x16_bf16 v[48:63], v[112:115], v[88:91], v[48:63]
	s_waitcnt vmcnt(18)
	v_mfma_f32_32x32x16_bf16 v[48:63], v[116:119], v[92:95], v[48:63]
	ds_read_b32 v233, v5 offset:1952
	ds_read_b32 v234, v5 offset:1956
	ds_read_b32 v235, v5 offset:1960
	ds_read_b32 v236, v5 offset:1964
	ds_read_b32 v237, v5 offset:1984
	ds_read_b32 v238, v5 offset:1988
	ds_read_b32 v239, v5 offset:1992
	ds_read_b32 v240, v5 offset:1996
	ds_read_b32 v241, v5 offset:2016
	ds_read_b32 v242, v5 offset:2020
	ds_read_b32 v243, v5 offset:2024
	ds_read_b32 v244, v5 offset:2028
	ds_read_b32 v245, v5 offset:2048
	ds_read_b32 v246, v5 offset:2052
	ds_read_b32 v247, v5 offset:2056
	ds_read_b32 v248, v5 offset:2060
	s_waitcnt lgkmcnt(0)
	v_fmac_f32_e32 v233, 0x3e38aa3b, v48
	s_nop 0
	v_cndmask_b32_e32 v1, v1, v233, vcc
	v_add_u32_e32 v3, 1, v6
	v_cmp_gt_u32_e32 vcc, 16, v3
	v_fmac_f32_e32 v234, 0x3e38aa3b, v49
	s_nop 0
	v_cndmask_b32_e32 v0, v0, v234, vcc
	v_add_u32_e32 v3, 2, v6
	v_cmp_gt_u32_e32 vcc, 16, v3
	v_mov_b32_e32 v3, 0xf149f2ca
	v_mov_b32_e32 v7, 0xf149f2ca
	v_fmac_f32_e32 v235, 0x3e38aa3b, v50
	s_nop 0
	v_cndmask_b32_e32 v7, v7, v235, vcc
	v_add_u32_e32 v8, 3, v6
	v_cmp_gt_u32_e32 vcc, 16, v8
	v_fmac_f32_e32 v236, 0x3e38aa3b, v51
	s_nop 0
	v_cndmask_b32_e32 v3, v3, v236, vcc
	v_add_u32_e32 v8, 8, v6
	v_cmp_gt_u32_e32 vcc, 16, v8
	v_mov_b32_e32 v8, 0xf149f2ca
	v_mov_b32_e32 v9, 0xf149f2ca
	v_fmac_f32_e32 v237, 0x3e38aa3b, v52
	s_nop 0
	v_cndmask_b32_e32 v9, v9, v237, vcc
	v_add_u32_e32 v10, 9, v6
	v_cmp_gt_u32_e32 vcc, 16, v10
	v_fmac_f32_e32 v238, 0x3e38aa3b, v53
	s_nop 0
	v_cndmask_b32_e32 v8, v8, v238, vcc
	v_add_u32_e32 v10, 10, v6
	v_cmp_gt_u32_e32 vcc, 16, v10
	v_mov_b32_e32 v10, 0xf149f2ca
	v_mov_b32_e32 v11, 0xf149f2ca
	v_fmac_f32_e32 v239, 0x3e38aa3b, v54
	s_nop 0
	v_cndmask_b32_e32 v11, v11, v239, vcc
	v_add_u32_e32 v12, 11, v6
	v_cmp_gt_u32_e32 vcc, 16, v12
	v_fmac_f32_e32 v240, 0x3e38aa3b, v55
	s_nop 0
	v_cndmask_b32_e32 v10, v10, v240, vcc
	v_cmp_lt_u32_e32 vcc, s52, v6
	v_mov_b32_e32 v13, 0xf149f2ca
	v_mov_b32_e32 v14, 0xf149f2ca
	v_fmac_f32_e32 v241, 0x3e38aa3b, v56
	s_nop 0
	v_cndmask_b32_e32 v14, v14, v241, vcc
	v_add_u32_e32 v12, 17, v6
	v_cmp_gt_u32_e32 vcc, 16, v12
	v_fmac_f32_e32 v242, 0x3e38aa3b, v57
	s_nop 0
	v_cndmask_b32_e32 v13, v13, v242, vcc
	v_add_u32_e32 v12, 18, v6
	v_cmp_gt_u32_e32 vcc, 16, v12
	v_mov_b32_e32 v12, 0xf149f2ca
	v_mov_b32_e32 v213, 0xf149f2ca
	v_fmac_f32_e32 v243, 0x3e38aa3b, v58
	s_nop 0
	v_cndmask_b32_e32 v213, v213, v243, vcc
	v_add_u32_e32 v15, 19, v6
	v_cmp_gt_u32_e32 vcc, 16, v15
	v_fmac_f32_e32 v244, 0x3e38aa3b, v59
	s_nop 0
	v_cndmask_b32_e32 v12, v12, v244, vcc
	v_add_u32_e32 v15, 24, v6
	v_cmp_gt_u32_e32 vcc, 16, v15
	v_mov_b32_e32 v15, 0xf149f2ca
	v_mov_b32_e32 v209, 0xf149f2ca
	v_fmac_f32_e32 v245, 0x3e38aa3b, v60
	s_nop 0
	v_cndmask_b32_e32 v209, v209, v245, vcc
	v_add_u32_e32 v48, 25, v6
	v_cmp_gt_u32_e32 vcc, 16, v48
	v_fmac_f32_e32 v246, 0x3e38aa3b, v61
	s_nop 0
	v_cndmask_b32_e32 v15, v15, v246, vcc
	v_add_u32_e32 v48, 26, v6
	v_cmp_gt_u32_e32 vcc, 16, v48
	v_mov_b32_e32 v226, 0xf149f2ca
	v_mov_b32_e32 v227, 0xf149f2ca
	v_fmac_f32_e32 v247, 0x3e38aa3b, v62
	s_nop 0
	v_cndmask_b32_e32 v227, v227, v247, vcc
	v_add_u32_e32 v6, 27, v6
	v_cmp_gt_u32_e32 vcc, 16, v6
	v_fmac_f32_e32 v248, 0x3e38aa3b, v63
	s_nop 0
	v_cndmask_b32_e32 v226, v226, v248, vcc
	v_max_f32_e32 v5, v0, v0
	v_max_f32_e32 v6, v1, v1
	v_max_f32_e32 v5, v6, v5
	v_max3_f32 v5, v5, v7, v3
	v_max3_f32 v5, v5, v9, v8
	v_max3_f32 v5, v5, v11, v10
	v_max3_f32 v5, v5, v14, v13
	v_max3_f32 v5, v5, v213, v12
	v_max3_f32 v5, v5, v209, v15
	v_max3_f32 v6, v5, v227, v226
	ds_bpermute_b32 v48, v224, v6
	v_mov_b64_e32 v[78:79], v[46:47]
	v_mov_b32_e32 v5, v201
	v_mov_b32_e32 v205, v4
	v_mov_b64_e32 v[76:77], v[44:45]
	s_waitcnt lgkmcnt(0)
	v_max3_f32 v6, v4, v6, v48
	v_mov_b64_e32 v[62:63], v[30:31]
	v_mov_b64_e32 v[74:75], v[42:43]
	v_mov_b64_e32 v[72:73], v[40:41]
	v_mov_b64_e32 v[70:71], v[38:39]
	v_mov_b64_e32 v[68:69], v[36:37]
	v_mov_b64_e32 v[66:67], v[34:35]
	v_mov_b64_e32 v[64:65], v[32:33]
	v_cmp_gt_f32_e32 vcc, v6, v4
	v_mov_b64_e32 v[60:61], v[28:29]
	v_mov_b64_e32 v[58:59], v[26:27]
	v_mov_b64_e32 v[56:57], v[24:25]
	v_mov_b64_e32 v[54:55], v[22:23]
	v_mov_b64_e32 v[52:53], v[20:21]
	v_mov_b64_e32 v[50:51], v[18:19]
	v_mov_b64_e32 v[48:49], v[16:17]
	s_cbranch_vccz .LBB0_910
	v_sub_f32_e32 v5, v4, v6
	v_exp_f32_e32 v64, v5
	v_mov_b32_e32 v205, v6
	v_mul_f32_e32 v5, v201, v64
	v_pk_mul_f32 v[62:63], v[30:31], v[64:65] op_sel_hi:[1,0]
	v_pk_mul_f32 v[60:61], v[28:29], v[64:65] op_sel_hi:[1,0]
	v_pk_mul_f32 v[58:59], v[26:27], v[64:65] op_sel_hi:[1,0]
	v_pk_mul_f32 v[56:57], v[24:25], v[64:65] op_sel_hi:[1,0]
	v_pk_mul_f32 v[54:55], v[22:23], v[64:65] op_sel_hi:[1,0]
	v_pk_mul_f32 v[52:53], v[20:21], v[64:65] op_sel_hi:[1,0]
	v_pk_mul_f32 v[50:51], v[18:19], v[64:65] op_sel_hi:[1,0]
	v_pk_mul_f32 v[48:49], v[16:17], v[64:65] op_sel_hi:[1,0]
	v_pk_mul_f32 v[78:79], v[46:47], v[64:65] op_sel_hi:[1,0]
	v_pk_mul_f32 v[76:77], v[44:45], v[64:65] op_sel_hi:[1,0]
	v_pk_mul_f32 v[74:75], v[42:43], v[64:65] op_sel_hi:[1,0]
	v_pk_mul_f32 v[72:73], v[40:41], v[64:65] op_sel_hi:[1,0]
	v_pk_mul_f32 v[70:71], v[38:39], v[64:65] op_sel_hi:[1,0]
	v_pk_mul_f32 v[68:69], v[36:37], v[64:65] op_sel_hi:[1,0]
	v_pk_mul_f32 v[66:67], v[34:35], v[64:65] op_sel_hi:[1,0]
	v_pk_mul_f32 v[64:65], v[32:33], v[64:65] op_sel_hi:[1,0]

.LBB0_914:
	s_cmp_gt_u32 s62, 14
	s_mov_b64 s[10:11], -1
	s_cbranch_scc0 .LBB0_983
	s_sub_i32 s10, s20, 19
	s_and_b32 s11, s10, 1
	s_lshr_b32 s10, s10, 1
	s_add_i32 s10, s10, s60
	v_lshl_or_b32 v0, s11, 5, v198
	s_mulk_i32 s10, 0x7c
	s_add_i32 s10, s15, s10
	v_sub_u32_e32 v1, v0, v193
	v_lshl_add_u32 v213, v1, 2, s10
	s_cmp_lg_u32 s11, s47
	v_sub_u32_e32 v226, v0, v223
	s_mov_b64 s[10:11], -1
	s_cbranch_scc0 .LBB0_940
	s_and_b64 vcc, exec, s[6:7]
	s_cbranch_vccz .LBB0_928
	s_waitcnt vmcnt(23)
	v_mfma_f32_32x32x16_bf16 v[4:19], v[124:127], v[80:83], 0
	v_add_u32_e32 v0, 24, v226
	v_cmp_gt_u32_e32 vcc, 16, v0
	v_mov_b32_e32 v0, 0xf149f2ca
	v_mov_b32_e32 v1, 0xf149f2ca
	s_waitcnt vmcnt(21)
	v_mfma_f32_32x32x16_bf16 v[4:19], v[136:139], v[84:87], v[4:19]
	s_waitcnt vmcnt(19)
	v_mfma_f32_32x32x16_bf16 v[4:19], v[144:147], v[88:91], v[4:19]
	s_waitcnt vmcnt(18)
	v_mfma_f32_32x32x16_bf16 v[4:19], v[148:151], v[92:95], v[4:19]
	ds_read_b32 v233, v213 offset:2048
	ds_read_b32 v234, v213 offset:2052
	ds_read_b32 v235, v213 offset:2056
	ds_read_b32 v236, v213 offset:2060
	s_waitcnt lgkmcnt(0)
	s_nop 7
	v_fmac_f32_e32 v233, 0x3e38aa3b, v16
	s_nop 0
	v_cndmask_b32_e32 v1, v1, v233, vcc
	v_add_u32_e32 v3, 25, v226
	v_cmp_gt_u32_e32 vcc, 16, v3
	v_fmac_f32_e32 v234, 0x3e38aa3b, v17
	s_nop 0
	v_cndmask_b32_e32 v0, v0, v234, vcc
	v_add_u32_e32 v3, 26, v226
	v_cmp_gt_u32_e32 vcc, 16, v3
	v_mov_b32_e32 v3, 0xf149f2ca
	s_nop 0
	v_mov_b32_e32 v5, 0xf149f2ca
	v_fmac_f32_e32 v235, 0x3e38aa3b, v18
	s_nop 0
	v_cndmask_b32_e32 v5, v5, v235, vcc
	v_add_u32_e32 v4, 27, v226
	v_cmp_gt_u32_e32 vcc, 16, v4
	v_fmac_f32_e32 v236, 0x3e38aa3b, v19
	s_nop 0
	v_cndmask_b32_e32 v3, v3, v236, vcc
	v_max_f32_e32 v4, v0, v0
	v_max_f32_e32 v6, v1, v1
	v_max_f32_e32 v4, v6, v4
	v_max3_f32 v7, v4, v5, v3
	ds_bpermute_b32 v8, v224, v7
	v_mov_b64_e32 v[32:33], v[64:65]
	v_mov_b64_e32 v[16:17], v[48:49]
	v_mov_b32_e32 v6, v209
	v_mov_b32_e32 v4, v205
	s_waitcnt lgkmcnt(0)
	v_max3_f32 v7, v205, v7, v8
	v_mov_b64_e32 v[34:35], v[66:67]
	v_mov_b64_e32 v[36:37], v[68:69]
	v_mov_b64_e32 v[38:39], v[70:71]
	v_mov_b64_e32 v[40:41], v[72:73]
	v_mov_b64_e32 v[42:43], v[74:75]
	v_mov_b64_e32 v[44:45], v[76:77]
	v_mov_b64_e32 v[46:47], v[78:79]
	v_cmp_gt_f32_e32 vcc, v7, v205
	v_mov_b64_e32 v[18:19], v[50:51]
	v_mov_b64_e32 v[20:21], v[52:53]
	v_mov_b64_e32 v[22:23], v[54:55]
	v_mov_b64_e32 v[24:25], v[56:57]
	v_mov_b64_e32 v[26:27], v[58:59]
	v_mov_b64_e32 v[28:29], v[60:61]
	v_mov_b64_e32 v[30:31], v[62:63]
	s_cbranch_vccz .LBB0_927
	v_sub_f32_e32 v4, v205, v7
	v_exp_f32_e32 v4, v4
	s_nop 0
	v_mul_f32_e32 v6, v209, v4
	v_pk_mul_f32 v[30:31], v[62:63], v[4:5] op_sel_hi:[1,0]
	v_pk_mul_f32 v[28:29], v[60:61], v[4:5] op_sel_hi:[1,0]
	v_pk_mul_f32 v[26:27], v[58:59], v[4:5] op_sel_hi:[1,0]
	v_pk_mul_f32 v[24:25], v[56:57], v[4:5] op_sel_hi:[1,0]
	v_pk_mul_f32 v[22:23], v[54:55], v[4:5] op_sel_hi:[1,0]
	v_pk_mul_f32 v[20:21], v[52:53], v[4:5] op_sel_hi:[1,0]
	v_pk_mul_f32 v[18:19], v[50:51], v[4:5] op_sel_hi:[1,0]
	v_pk_mul_f32 v[16:17], v[48:49], v[4:5] op_sel_hi:[1,0]
	v_pk_mul_f32 v[46:47], v[78:79], v[4:5] op_sel_hi:[1,0]
	v_pk_mul_f32 v[44:45], v[76:77], v[4:5] op_sel_hi:[1,0]
	v_pk_mul_f32 v[42:43], v[74:75], v[4:5] op_sel_hi:[1,0]
	v_pk_mul_f32 v[40:41], v[72:73], v[4:5] op_sel_hi:[1,0]
	v_pk_mul_f32 v[38:39], v[70:71], v[4:5] op_sel_hi:[1,0]
	v_pk_mul_f32 v[36:37], v[68:69], v[4:5] op_sel_hi:[1,0]
	v_pk_mul_f32 v[34:35], v[66:67], v[4:5] op_sel_hi:[1,0]
	v_pk_mul_f32 v[32:33], v[64:65], v[4:5] op_sel_hi:[1,0]
	v_mov_b32_e32 v4, v7

.LBB0_928:
	s_and_b64 vcc, exec, s[10:11]
	s_cbranch_vccz .LBB0_1055
	s_waitcnt vmcnt(23)
	v_mfma_f32_32x32x16_bf16 v[4:19], v[124:127], v[80:83], 0
	v_cmp_gt_u32_e32 vcc, 16, v226
	v_mov_b32_e32 v1, 0xf149f2ca
	v_mov_b32_e32 v0, 0xf149f2ca
	s_waitcnt vmcnt(21)
	v_mfma_f32_32x32x16_bf16 v[4:19], v[136:139], v[84:87], v[4:19]
	s_waitcnt vmcnt(19)
	v_mfma_f32_32x32x16_bf16 v[4:19], v[144:147], v[88:91], v[4:19]
	s_waitcnt vmcnt(18)
	v_mfma_f32_32x32x16_bf16 v[4:19], v[148:151], v[92:95], v[4:19]
	ds_read_b32 v233, v213 offset:1952
	ds_read_b32 v234, v213 offset:1956
	ds_read_b32 v235, v213 offset:1960
	ds_read_b32 v236, v213 offset:1964
	s_waitcnt lgkmcnt(0)
	s_nop 7
	v_fmac_f32_e32 v233, 0x3e38aa3b, v4
	s_nop 0
	v_cndmask_b32_e32 v0, v0, v233, vcc
	v_add_u32_e32 v3, 1, v226
	v_cmp_gt_u32_e32 vcc, 16, v3
	v_fmac_f32_e32 v234, 0x3e38aa3b, v5
	s_nop 0
	v_cndmask_b32_e32 v1, v1, v234, vcc
	v_add_u32_e32 v3, 2, v226
	v_cmp_gt_u32_e32 vcc, 16, v3
	s_nop 1
	v_mov_b32_e32 v5, 0xf149f2ca
	v_mov_b32_e32 v3, 0xf149f2ca
	v_fmac_f32_e32 v235, 0x3e38aa3b, v6
	s_nop 0
	v_cndmask_b32_e32 v3, v3, v235, vcc
	v_add_u32_e32 v4, 3, v226
	v_cmp_gt_u32_e32 vcc, 16, v4
	v_fmac_f32_e32 v236, 0x3e38aa3b, v7
	s_nop 0
	v_cndmask_b32_e32 v5, v5, v236, vcc
	v_max_f32_e32 v4, v1, v1
	v_max_f32_e32 v6, v0, v0
	v_max_f32_e32 v4, v6, v4
	v_max3_f32 v7, v4, v3, v5
	ds_bpermute_b32 v8, v224, v7
	v_mov_b64_e32 v[32:33], v[64:65]
	v_mov_b64_e32 v[16:17], v[48:49]
	v_mov_b32_e32 v6, v209
	v_mov_b32_e32 v4, v205
	s_waitcnt lgkmcnt(0)
	v_max3_f32 v7, v205, v7, v8
	v_mov_b64_e32 v[34:35], v[66:67]
	v_mov_b64_e32 v[36:37], v[68:69]
	v_mov_b64_e32 v[38:39], v[70:71]
	v_mov_b64_e32 v[40:41], v[72:73]
	v_mov_b64_e32 v[42:43], v[74:75]
	v_mov_b64_e32 v[44:45], v[76:77]
	v_mov_b64_e32 v[46:47], v[78:79]
	v_cmp_gt_f32_e32 vcc, v7, v205
	v_mov_b64_e32 v[18:19], v[50:51]
	v_mov_b64_e32 v[20:21], v[52:53]
	v_mov_b64_e32 v[22:23], v[54:55]
	v_mov_b64_e32 v[24:25], v[56:57]
	v_mov_b64_e32 v[26:27], v[58:59]
	v_mov_b64_e32 v[28:29], v[60:61]
	v_mov_b64_e32 v[30:31], v[62:63]
	s_cbranch_vccz .LBB0_939
	v_sub_f32_e32 v4, v205, v7
	v_exp_f32_e32 v4, v4
	s_nop 0
	v_mul_f32_e32 v6, v209, v4
	v_pk_mul_f32 v[30:31], v[62:63], v[4:5] op_sel_hi:[1,0]
	v_pk_mul_f32 v[28:29], v[60:61], v[4:5] op_sel_hi:[1,0]
	v_pk_mul_f32 v[26:27], v[58:59], v[4:5] op_sel_hi:[1,0]
	v_pk_mul_f32 v[24:25], v[56:57], v[4:5] op_sel_hi:[1,0]
	v_pk_mul_f32 v[22:23], v[54:55], v[4:5] op_sel_hi:[1,0]
	v_pk_mul_f32 v[20:21], v[52:53], v[4:5] op_sel_hi:[1,0]
	v_pk_mul_f32 v[18:19], v[50:51], v[4:5] op_sel_hi:[1,0]
	v_pk_mul_f32 v[16:17], v[48:49], v[4:5] op_sel_hi:[1,0]
	v_pk_mul_f32 v[46:47], v[78:79], v[4:5] op_sel_hi:[1,0]
	v_pk_mul_f32 v[44:45], v[76:77], v[4:5] op_sel_hi:[1,0]
	v_pk_mul_f32 v[42:43], v[74:75], v[4:5] op_sel_hi:[1,0]
	v_pk_mul_f32 v[40:41], v[72:73], v[4:5] op_sel_hi:[1,0]
	v_pk_mul_f32 v[38:39], v[70:71], v[4:5] op_sel_hi:[1,0]
	v_pk_mul_f32 v[36:37], v[68:69], v[4:5] op_sel_hi:[1,0]
	v_pk_mul_f32 v[34:35], v[66:67], v[4:5] op_sel_hi:[1,0]
	v_pk_mul_f32 v[32:33], v[64:65], v[4:5] op_sel_hi:[1,0]
	v_mov_b32_e32 v4, v7

.LBB0_941:
	s_waitcnt vmcnt(23)
	v_mfma_f32_32x32x16_bf16 v[4:19], v[124:127], v[80:83], 0
	v_cmp_gt_u32_e32 vcc, 16, v226
	v_mov_b32_e32 v0, 0xf149f2ca
	v_mov_b32_e32 v1, 0xf149f2ca
	s_waitcnt vmcnt(21)
	v_mfma_f32_32x32x16_bf16 v[4:19], v[136:139], v[84:87], v[4:19]
	s_waitcnt vmcnt(19)
	v_mfma_f32_32x32x16_bf16 v[4:19], v[144:147], v[88:91], v[4:19]
	s_waitcnt vmcnt(18)
	v_mfma_f32_32x32x16_bf16 v[4:19], v[148:151], v[92:95], v[4:19]
	ds_read_b32 v233, v213 offset:1952
	ds_read_b32 v234, v213 offset:1956
	ds_read_b32 v235, v213 offset:1960
	ds_read_b32 v236, v213 offset:1964
	ds_read_b32 v237, v213 offset:1984
	ds_read_b32 v238, v213 offset:1988
	ds_read_b32 v239, v213 offset:1992
	ds_read_b32 v240, v213 offset:1996
	ds_read_b32 v241, v213 offset:2016
	ds_read_b32 v242, v213 offset:2020
	ds_read_b32 v243, v213 offset:2024
	ds_read_b32 v244, v213 offset:2028
	ds_read_b32 v245, v213 offset:2048
	ds_read_b32 v246, v213 offset:2052
	ds_read_b32 v247, v213 offset:2056
	ds_read_b32 v248, v213 offset:2060
	s_waitcnt lgkmcnt(0)
	v_fmac_f32_e32 v233, 0x3e38aa3b, v4
	s_nop 0
	v_cndmask_b32_e32 v1, v1, v233, vcc
	v_add_u32_e32 v3, 1, v226
	v_cmp_gt_u32_e32 vcc, 16, v3
	v_fmac_f32_e32 v234, 0x3e38aa3b, v5
	s_nop 0
	v_cndmask_b32_e32 v0, v0, v234, vcc
	v_add_u32_e32 v3, 2, v226
	v_cmp_gt_u32_e32 vcc, 16, v3
	v_mov_b32_e32 v3, 0xf149f2ca
	s_nop 0
	v_mov_b32_e32 v5, 0xf149f2ca
	v_fmac_f32_e32 v235, 0x3e38aa3b, v6
	s_nop 0
	v_cndmask_b32_e32 v5, v5, v235, vcc
	v_add_u32_e32 v4, 3, v226
	v_cmp_gt_u32_e32 vcc, 16, v4
	v_fmac_f32_e32 v236, 0x3e38aa3b, v7
	s_nop 0
	v_cndmask_b32_e32 v3, v3, v236, vcc
	v_add_u32_e32 v4, 8, v226
	v_cmp_gt_u32_e32 vcc, 16, v4
	v_mov_b32_e32 v6, 0xf149f2ca
	v_mov_b32_e32 v7, 0xf149f2ca
	v_fmac_f32_e32 v237, 0x3e38aa3b, v8
	s_nop 0
	v_cndmask_b32_e32 v7, v7, v237, vcc
	v_add_u32_e32 v4, 9, v226
	v_cmp_gt_u32_e32 vcc, 16, v4
	v_fmac_f32_e32 v238, 0x3e38aa3b, v9
	s_nop 0
	v_cndmask_b32_e32 v6, v6, v238, vcc
	v_add_u32_e32 v4, 10, v226
	v_cmp_gt_u32_e32 vcc, 16, v4
	v_mov_b32_e32 v8, 0xf149f2ca
	v_mov_b32_e32 v9, 0xf149f2ca
	v_fmac_f32_e32 v239, 0x3e38aa3b, v10
	s_nop 0
	v_cndmask_b32_e32 v9, v9, v239, vcc
	v_add_u32_e32 v4, 11, v226
	v_cmp_gt_u32_e32 vcc, 16, v4
	v_fmac_f32_e32 v240, 0x3e38aa3b, v11
	s_nop 0
	v_cndmask_b32_e32 v8, v8, v240, vcc
	v_cmp_lt_u32_e32 vcc, s52, v226
	v_mov_b32_e32 v11, 0xf149f2ca
	v_mov_b32_e32 v201, 0xf149f2ca
	v_fmac_f32_e32 v241, 0x3e38aa3b, v12
	s_nop 0
	v_cndmask_b32_e32 v201, v201, v241, vcc
	v_add_u32_e32 v4, 17, v226
	v_cmp_gt_u32_e32 vcc, 16, v4
	v_fmac_f32_e32 v242, 0x3e38aa3b, v13
	s_nop 0
	v_cndmask_b32_e32 v11, v11, v242, vcc
	v_add_u32_e32 v4, 18, v226
	v_cmp_gt_u32_e32 vcc, 16, v4
	v_mov_b32_e32 v10, 0xf149f2ca
	v_mov_b32_e32 v227, 0xf149f2ca
	v_fmac_f32_e32 v243, 0x3e38aa3b, v14
	s_nop 0
	v_cndmask_b32_e32 v227, v227, v243, vcc
	v_add_u32_e32 v4, 19, v226
	v_cmp_gt_u32_e32 vcc, 16, v4
	v_fmac_f32_e32 v244, 0x3e38aa3b, v15
	s_nop 0
	v_cndmask_b32_e32 v10, v10, v244, vcc
	v_add_u32_e32 v4, 24, v226
	v_cmp_gt_u32_e32 vcc, 16, v4
	v_mov_b32_e32 v12, 0xf149f2ca
	v_mov_b32_e32 v13, 0xf149f2ca
	v_fmac_f32_e32 v245, 0x3e38aa3b, v16
	s_nop 0
	v_cndmask_b32_e32 v13, v13, v245, vcc
	v_add_u32_e32 v4, 25, v226
	v_cmp_gt_u32_e32 vcc, 16, v4
	v_fmac_f32_e32 v246, 0x3e38aa3b, v17
	s_nop 0
	v_cndmask_b32_e32 v12, v12, v246, vcc
	v_add_u32_e32 v4, 26, v226
	v_cmp_gt_u32_e32 vcc, 16, v4
	v_mov_b32_e32 v14, 0xf149f2ca
	v_mov_b32_e32 v15, 0xf149f2ca
	v_fmac_f32_e32 v247, 0x3e38aa3b, v18
	s_nop 0
	v_cndmask_b32_e32 v15, v15, v247, vcc
	v_add_u32_e32 v4, 27, v226
	v_cmp_gt_u32_e32 vcc, 16, v4
	v_fmac_f32_e32 v248, 0x3e38aa3b, v19
	s_nop 0
	v_cndmask_b32_e32 v14, v14, v248, vcc
	v_max_f32_e32 v4, v0, v0
	v_max_f32_e32 v16, v1, v1
	v_max_f32_e32 v4, v16, v4
	v_max3_f32 v4, v4, v5, v3
	v_max3_f32 v4, v4, v7, v6
	v_max3_f32 v4, v4, v9, v8
	v_max3_f32 v4, v4, v201, v11
	v_max3_f32 v4, v4, v227, v10
	v_max3_f32 v4, v4, v13, v12
	v_max3_f32 v16, v4, v15, v14
	ds_bpermute_b32 v17, v224, v16
	v_mov_b64_e32 v[32:33], v[64:65]
	v_mov_b32_e32 v213, v209
	v_mov_b32_e32 v4, v205
	v_mov_b64_e32 v[34:35], v[66:67]
	s_waitcnt lgkmcnt(0)
	v_max3_f32 v226, v205, v16, v17
	v_mov_b64_e32 v[16:17], v[48:49]
	v_mov_b64_e32 v[36:37], v[68:69]
	v_mov_b64_e32 v[38:39], v[70:71]
	v_mov_b64_e32 v[40:41], v[72:73]
	v_mov_b64_e32 v[42:43], v[74:75]
	v_mov_b64_e32 v[44:45], v[76:77]
	v_mov_b64_e32 v[46:47], v[78:79]
	v_cmp_gt_f32_e32 vcc, v226, v205
	v_mov_b64_e32 v[18:19], v[50:51]
	v_mov_b64_e32 v[20:21], v[52:53]
	v_mov_b64_e32 v[22:23], v[54:55]
	v_mov_b64_e32 v[24:25], v[56:57]
	v_mov_b64_e32 v[26:27], v[58:59]
	v_mov_b64_e32 v[28:29], v[60:61]
	v_mov_b64_e32 v[30:31], v[62:63]
	s_cbranch_vccz .LBB0_975
	v_sub_f32_e32 v4, v205, v226
	v_exp_f32_e32 v4, v4
	s_nop 0
	v_mul_f32_e32 v213, v209, v4
	v_pk_mul_f32 v[30:31], v[62:63], v[4:5] op_sel_hi:[1,0]
	v_pk_mul_f32 v[28:29], v[60:61], v[4:5] op_sel_hi:[1,0]
	v_pk_mul_f32 v[26:27], v[58:59], v[4:5] op_sel_hi:[1,0]
	v_pk_mul_f32 v[24:25], v[56:57], v[4:5] op_sel_hi:[1,0]
	v_pk_mul_f32 v[22:23], v[54:55], v[4:5] op_sel_hi:[1,0]
	v_pk_mul_f32 v[20:21], v[52:53], v[4:5] op_sel_hi:[1,0]
	v_pk_mul_f32 v[18:19], v[50:51], v[4:5] op_sel_hi:[1,0]
	v_pk_mul_f32 v[16:17], v[48:49], v[4:5] op_sel_hi:[1,0]
	v_pk_mul_f32 v[46:47], v[78:79], v[4:5] op_sel_hi:[1,0]
	v_pk_mul_f32 v[44:45], v[76:77], v[4:5] op_sel_hi:[1,0]
	v_pk_mul_f32 v[42:43], v[74:75], v[4:5] op_sel_hi:[1,0]
	v_pk_mul_f32 v[40:41], v[72:73], v[4:5] op_sel_hi:[1,0]
	v_pk_mul_f32 v[38:39], v[70:71], v[4:5] op_sel_hi:[1,0]
	v_pk_mul_f32 v[36:37], v[68:69], v[4:5] op_sel_hi:[1,0]
	v_pk_mul_f32 v[34:35], v[66:67], v[4:5] op_sel_hi:[1,0]
	v_pk_mul_f32 v[32:33], v[64:65], v[4:5] op_sel_hi:[1,0]
	v_mov_b32_e32 v4, v226

.LBB0_988:
	s_cmp_gt_u32 s62, 13
	s_mov_b64 s[10:11], -1
	s_cbranch_scc0 .LBB0_1051
	s_sub_i32 s10, s20, 18
	s_lshr_b32 s10, s10, 1
	s_and_b32 s11, s62, 1
	s_add_i32 s10, s10, s60
	v_lshl_or_b32 v0, s11, 5, v198
	s_mulk_i32 s10, 0x7c
	s_add_i32 s10, s15, s10
	v_sub_u32_e32 v1, v0, v193
	v_lshl_add_u32 v5, v1, 2, s10
	s_cmp_lg_u32 s11, s47
	v_sub_u32_e32 v6, v0, v223
	s_mov_b64 s[10:11], -1
	s_cbranch_scc0 .LBB0_1014
	s_and_b64 vcc, exec, s[6:7]
	s_cbranch_vccz .LBB0_1002
	s_waitcnt vmcnt(23)
	v_mfma_f32_32x32x16_bf16 v[48:63], v[160:163], v[80:83], 0
	v_add_u32_e32 v0, 24, v6
	v_cmp_gt_u32_e32 vcc, 16, v0
	v_mov_b32_e32 v0, 0xf149f2ca
	v_mov_b32_e32 v1, 0xf149f2ca
	s_waitcnt vmcnt(22)
	v_mfma_f32_32x32x16_bf16 v[48:63], v[164:167], v[84:87], v[48:63]
	s_waitcnt vmcnt(19)
	v_mfma_f32_32x32x16_bf16 v[48:63], v[168:171], v[88:91], v[48:63]
	s_waitcnt vmcnt(18)
	v_mfma_f32_32x32x16_bf16 v[48:63], v[180:183], v[92:95], v[48:63]
	ds_read_b32 v233, v5 offset:2048
	ds_read_b32 v234, v5 offset:2052
	ds_read_b32 v235, v5 offset:2056
	ds_read_b32 v236, v5 offset:2060
	s_waitcnt lgkmcnt(0)
	s_nop 7
	v_fmac_f32_e32 v233, 0x3e38aa3b, v60
	s_nop 0
	v_cndmask_b32_e32 v1, v1, v233, vcc
	v_add_u32_e32 v3, 25, v6
	v_cmp_gt_u32_e32 vcc, 16, v3
	v_fmac_f32_e32 v234, 0x3e38aa3b, v61
	s_nop 0
	v_cndmask_b32_e32 v0, v0, v234, vcc
	v_add_u32_e32 v3, 26, v6
	v_cmp_gt_u32_e32 vcc, 16, v3
	v_mov_b32_e32 v3, 0xf149f2ca
	v_mov_b32_e32 v7, 0xf149f2ca
	v_fmac_f32_e32 v235, 0x3e38aa3b, v62
	s_nop 0
	v_cndmask_b32_e32 v7, v7, v235, vcc
	v_add_u32_e32 v8, 27, v6
	v_cmp_gt_u32_e32 vcc, 16, v8
	v_fmac_f32_e32 v236, 0x3e38aa3b, v63
	s_nop 0
	v_cndmask_b32_e32 v3, v3, v236, vcc
	v_max_f32_e32 v8, v0, v0
	v_max_f32_e32 v9, v1, v1
	v_max_f32_e32 v8, v9, v8
	v_max3_f32 v9, v8, v7, v3
	ds_bpermute_b32 v11, v224, v9
	v_mov_b64_e32 v[78:79], v[46:47]
	v_mov_b64_e32 v[62:63], v[30:31]
	v_mov_b32_e32 v8, v201
	v_mov_b32_e32 v10, v4
	s_waitcnt lgkmcnt(0)
	v_max3_f32 v9, v4, v9, v11
	v_mov_b64_e32 v[76:77], v[44:45]
	v_mov_b64_e32 v[74:75], v[42:43]
	v_mov_b64_e32 v[72:73], v[40:41]
	v_mov_b64_e32 v[70:71], v[38:39]
	v_mov_b64_e32 v[68:69], v[36:37]
	v_mov_b64_e32 v[66:67], v[34:35]
	v_mov_b64_e32 v[64:65], v[32:33]
	v_cmp_gt_f32_e32 vcc, v9, v4
	v_mov_b64_e32 v[60:61], v[28:29]
	v_mov_b64_e32 v[58:59], v[26:27]
	v_mov_b64_e32 v[56:57], v[24:25]
	v_mov_b64_e32 v[54:55], v[22:23]
	v_mov_b64_e32 v[52:53], v[20:21]
	v_mov_b64_e32 v[50:51], v[18:19]
	v_mov_b64_e32 v[48:49], v[16:17]
	s_cbranch_vccz .LBB0_1001
	v_sub_f32_e32 v8, v4, v9
	v_exp_f32_e32 v10, v8
	s_nop 0
	v_mul_f32_e32 v8, v201, v10
	v_pk_mul_f32 v[62:63], v[30:31], v[10:11] op_sel_hi:[1,0]
	v_pk_mul_f32 v[60:61], v[28:29], v[10:11] op_sel_hi:[1,0]
	v_pk_mul_f32 v[58:59], v[26:27], v[10:11] op_sel_hi:[1,0]
	v_pk_mul_f32 v[56:57], v[24:25], v[10:11] op_sel_hi:[1,0]
	v_pk_mul_f32 v[54:55], v[22:23], v[10:11] op_sel_hi:[1,0]
	v_pk_mul_f32 v[52:53], v[20:21], v[10:11] op_sel_hi:[1,0]
	v_pk_mul_f32 v[50:51], v[18:19], v[10:11] op_sel_hi:[1,0]
	v_pk_mul_f32 v[48:49], v[16:17], v[10:11] op_sel_hi:[1,0]
	v_pk_mul_f32 v[78:79], v[46:47], v[10:11] op_sel_hi:[1,0]
	v_pk_mul_f32 v[76:77], v[44:45], v[10:11] op_sel_hi:[1,0]
	v_pk_mul_f32 v[74:75], v[42:43], v[10:11] op_sel_hi:[1,0]
	v_pk_mul_f32 v[72:73], v[40:41], v[10:11] op_sel_hi:[1,0]
	v_pk_mul_f32 v[70:71], v[38:39], v[10:11] op_sel_hi:[1,0]
	v_pk_mul_f32 v[68:69], v[36:37], v[10:11] op_sel_hi:[1,0]
	v_pk_mul_f32 v[66:67], v[34:35], v[10:11] op_sel_hi:[1,0]
	v_pk_mul_f32 v[64:65], v[32:33], v[10:11] op_sel_hi:[1,0]
	v_mov_b32_e32 v10, v9

.LBB0_1002:
	s_and_b64 vcc, exec, s[10:11]
	s_cbranch_vccz .LBB0_1056
	s_waitcnt vmcnt(23)
	v_mfma_f32_32x32x16_bf16 v[48:63], v[160:163], v[80:83], 0
	v_cmp_gt_u32_e32 vcc, 16, v6
	v_mov_b32_e32 v1, 0xf149f2ca
	v_mov_b32_e32 v0, 0xf149f2ca
	s_waitcnt vmcnt(22)
	v_mfma_f32_32x32x16_bf16 v[48:63], v[164:167], v[84:87], v[48:63]
	s_waitcnt vmcnt(19)
	v_mfma_f32_32x32x16_bf16 v[48:63], v[168:171], v[88:91], v[48:63]
	s_waitcnt vmcnt(18)
	v_mfma_f32_32x32x16_bf16 v[48:63], v[180:183], v[92:95], v[48:63]
	ds_read_b32 v233, v5 offset:1952
	ds_read_b32 v234, v5 offset:1956
	ds_read_b32 v235, v5 offset:1960
	ds_read_b32 v236, v5 offset:1964
	s_waitcnt lgkmcnt(0)
	s_nop 7
	v_fmac_f32_e32 v233, 0x3e38aa3b, v48
	s_nop 0
	v_cndmask_b32_e32 v0, v0, v233, vcc
	v_add_u32_e32 v3, 1, v6
	v_cmp_gt_u32_e32 vcc, 16, v3
	v_fmac_f32_e32 v234, 0x3e38aa3b, v49
	s_nop 0
	v_cndmask_b32_e32 v1, v1, v234, vcc
	v_add_u32_e32 v3, 2, v6
	v_cmp_gt_u32_e32 vcc, 16, v3
	v_mov_b32_e32 v7, 0xf149f2ca
	v_mov_b32_e32 v3, 0xf149f2ca
	v_fmac_f32_e32 v235, 0x3e38aa3b, v50
	s_nop 0
	v_cndmask_b32_e32 v3, v3, v235, vcc
	v_add_u32_e32 v8, 3, v6
	v_cmp_gt_u32_e32 vcc, 16, v8
	v_fmac_f32_e32 v236, 0x3e38aa3b, v51
	s_nop 0
	v_cndmask_b32_e32 v7, v7, v236, vcc
	v_max_f32_e32 v8, v1, v1
	v_max_f32_e32 v9, v0, v0
	v_max_f32_e32 v8, v9, v8
	v_max3_f32 v9, v8, v3, v7
	ds_bpermute_b32 v11, v224, v9
	v_mov_b64_e32 v[78:79], v[46:47]
	v_mov_b64_e32 v[62:63], v[30:31]
	v_mov_b32_e32 v8, v201
	v_mov_b32_e32 v10, v4
	s_waitcnt lgkmcnt(0)
	v_max3_f32 v9, v4, v9, v11
	v_mov_b64_e32 v[76:77], v[44:45]
	v_mov_b64_e32 v[74:75], v[42:43]
	v_mov_b64_e32 v[72:73], v[40:41]
	v_mov_b64_e32 v[70:71], v[38:39]
	v_mov_b64_e32 v[68:69], v[36:37]
	v_mov_b64_e32 v[66:67], v[34:35]
	v_mov_b64_e32 v[64:65], v[32:33]
	v_cmp_gt_f32_e32 vcc, v9, v4
	v_mov_b64_e32 v[60:61], v[28:29]
	v_mov_b64_e32 v[58:59], v[26:27]
	v_mov_b64_e32 v[56:57], v[24:25]
	v_mov_b64_e32 v[54:55], v[22:23]
	v_mov_b64_e32 v[52:53], v[20:21]
	v_mov_b64_e32 v[50:51], v[18:19]
	v_mov_b64_e32 v[48:49], v[16:17]
	s_cbranch_vccz .LBB0_1013
	v_sub_f32_e32 v8, v4, v9
	v_exp_f32_e32 v10, v8
	s_nop 0
	v_mul_f32_e32 v8, v201, v10
	v_pk_mul_f32 v[62:63], v[30:31], v[10:11] op_sel_hi:[1,0]
	v_pk_mul_f32 v[60:61], v[28:29], v[10:11] op_sel_hi:[1,0]
	v_pk_mul_f32 v[58:59], v[26:27], v[10:11] op_sel_hi:[1,0]
	v_pk_mul_f32 v[56:57], v[24:25], v[10:11] op_sel_hi:[1,0]
	v_pk_mul_f32 v[54:55], v[22:23], v[10:11] op_sel_hi:[1,0]
	v_pk_mul_f32 v[52:53], v[20:21], v[10:11] op_sel_hi:[1,0]
	v_pk_mul_f32 v[50:51], v[18:19], v[10:11] op_sel_hi:[1,0]
	v_pk_mul_f32 v[48:49], v[16:17], v[10:11] op_sel_hi:[1,0]
	v_pk_mul_f32 v[78:79], v[46:47], v[10:11] op_sel_hi:[1,0]
	v_pk_mul_f32 v[76:77], v[44:45], v[10:11] op_sel_hi:[1,0]
	v_pk_mul_f32 v[74:75], v[42:43], v[10:11] op_sel_hi:[1,0]
	v_pk_mul_f32 v[72:73], v[40:41], v[10:11] op_sel_hi:[1,0]
	v_pk_mul_f32 v[70:71], v[38:39], v[10:11] op_sel_hi:[1,0]
	v_pk_mul_f32 v[68:69], v[36:37], v[10:11] op_sel_hi:[1,0]
	v_pk_mul_f32 v[66:67], v[34:35], v[10:11] op_sel_hi:[1,0]
	v_pk_mul_f32 v[64:65], v[32:33], v[10:11] op_sel_hi:[1,0]
	v_mov_b32_e32 v10, v9

.LBB0_1015:
	s_waitcnt vmcnt(23)
	v_mfma_f32_32x32x16_bf16 v[48:63], v[160:163], v[80:83], 0
	v_cmp_gt_u32_e32 vcc, 16, v6
	v_mov_b32_e32 v0, 0xf149f2ca
	v_mov_b32_e32 v1, 0xf149f2ca
	s_waitcnt vmcnt(22)
	v_mfma_f32_32x32x16_bf16 v[48:63], v[164:167], v[84:87], v[48:63]
	s_waitcnt vmcnt(19)
	v_mfma_f32_32x32x16_bf16 v[48:63], v[168:171], v[88:91], v[48:63]
	s_waitcnt vmcnt(18)
	v_mfma_f32_32x32x16_bf16 v[48:63], v[180:183], v[92:95], v[48:63]
	ds_read_b32 v233, v5 offset:1952
	ds_read_b32 v234, v5 offset:1956
	ds_read_b32 v235, v5 offset:1960
	ds_read_b32 v236, v5 offset:1964
	ds_read_b32 v237, v5 offset:1984
	ds_read_b32 v238, v5 offset:1988
	ds_read_b32 v239, v5 offset:1992
	ds_read_b32 v240, v5 offset:1996
	ds_read_b32 v241, v5 offset:2016
	ds_read_b32 v242, v5 offset:2020
	ds_read_b32 v243, v5 offset:2024
	ds_read_b32 v244, v5 offset:2028
	ds_read_b32 v245, v5 offset:2048
	ds_read_b32 v246, v5 offset:2052
	ds_read_b32 v247, v5 offset:2056
	ds_read_b32 v248, v5 offset:2060
	s_waitcnt lgkmcnt(0)
	v_fmac_f32_e32 v233, 0x3e38aa3b, v48
	s_nop 0
	v_cndmask_b32_e32 v1, v1, v233, vcc
	v_add_u32_e32 v3, 1, v6
	v_cmp_gt_u32_e32 vcc, 16, v3
	v_fmac_f32_e32 v234, 0x3e38aa3b, v49
	s_nop 0
	v_cndmask_b32_e32 v0, v0, v234, vcc
	v_add_u32_e32 v3, 2, v6
	v_cmp_gt_u32_e32 vcc, 16, v3
	v_mov_b32_e32 v3, 0xf149f2ca
	v_mov_b32_e32 v7, 0xf149f2ca
	v_fmac_f32_e32 v235, 0x3e38aa3b, v50
	s_nop 0
	v_cndmask_b32_e32 v7, v7, v235, vcc
	v_add_u32_e32 v8, 3, v6
	v_cmp_gt_u32_e32 vcc, 16, v8
	v_fmac_f32_e32 v236, 0x3e38aa3b, v51
	s_nop 0
	v_cndmask_b32_e32 v3, v3, v236, vcc
	v_add_u32_e32 v8, 8, v6
	v_cmp_gt_u32_e32 vcc, 16, v8
	v_mov_b32_e32 v8, 0xf149f2ca
	v_mov_b32_e32 v9, 0xf149f2ca
	v_fmac_f32_e32 v237, 0x3e38aa3b, v52
	s_nop 0
	v_cndmask_b32_e32 v9, v9, v237, vcc
	v_add_u32_e32 v10, 9, v6
	v_cmp_gt_u32_e32 vcc, 16, v10
	v_fmac_f32_e32 v238, 0x3e38aa3b, v53
	s_nop 0
	v_cndmask_b32_e32 v8, v8, v238, vcc
	v_add_u32_e32 v10, 10, v6
	v_cmp_gt_u32_e32 vcc, 16, v10
	v_mov_b32_e32 v11, 0xf149f2ca
	v_mov_b32_e32 v12, 0xf149f2ca
	v_fmac_f32_e32 v239, 0x3e38aa3b, v54
	s_nop 0
	v_cndmask_b32_e32 v12, v12, v239, vcc
	v_add_u32_e32 v10, 11, v6
	v_cmp_gt_u32_e32 vcc, 16, v10
	v_fmac_f32_e32 v240, 0x3e38aa3b, v55
	s_nop 0
	v_cndmask_b32_e32 v11, v11, v240, vcc
	v_cmp_lt_u32_e32 vcc, s52, v6
	v_mov_b32_e32 v14, 0xf149f2ca
	v_mov_b32_e32 v15, 0xf149f2ca
	v_fmac_f32_e32 v241, 0x3e38aa3b, v56
	s_nop 0
	v_cndmask_b32_e32 v15, v15, v241, vcc
	v_add_u32_e32 v10, 17, v6
	v_cmp_gt_u32_e32 vcc, 16, v10
	v_fmac_f32_e32 v242, 0x3e38aa3b, v57
	s_nop 0
	v_cndmask_b32_e32 v14, v14, v242, vcc
	v_add_u32_e32 v10, 18, v6
	v_cmp_gt_u32_e32 vcc, 16, v10
	v_mov_b32_e32 v13, 0xf149f2ca
	v_mov_b32_e32 v213, 0xf149f2ca
	v_fmac_f32_e32 v243, 0x3e38aa3b, v58
	s_nop 0
	v_cndmask_b32_e32 v213, v213, v243, vcc
	v_add_u32_e32 v10, 19, v6
	v_cmp_gt_u32_e32 vcc, 16, v10
	v_fmac_f32_e32 v244, 0x3e38aa3b, v59
	s_nop 0
	v_cndmask_b32_e32 v13, v13, v244, vcc
	v_add_u32_e32 v10, 24, v6
	v_cmp_gt_u32_e32 vcc, 16, v10
	v_mov_b32_e32 v205, 0xf149f2ca
	v_mov_b32_e32 v209, 0xf149f2ca
	v_fmac_f32_e32 v245, 0x3e38aa3b, v60
	s_nop 0
	v_cndmask_b32_e32 v209, v209, v245, vcc
	v_add_u32_e32 v10, 25, v6
	v_cmp_gt_u32_e32 vcc, 16, v10
	v_fmac_f32_e32 v246, 0x3e38aa3b, v61
	s_nop 0
	v_cndmask_b32_e32 v205, v205, v246, vcc
	v_add_u32_e32 v10, 26, v6
	v_cmp_gt_u32_e32 vcc, 16, v10
	v_mov_b32_e32 v226, 0xf149f2ca
	v_mov_b32_e32 v227, 0xf149f2ca
	v_fmac_f32_e32 v247, 0x3e38aa3b, v62
	s_nop 0
	v_cndmask_b32_e32 v227, v227, v247, vcc
	v_add_u32_e32 v6, 27, v6
	v_cmp_gt_u32_e32 vcc, 16, v6
	v_fmac_f32_e32 v248, 0x3e38aa3b, v63
	s_nop 0
	v_cndmask_b32_e32 v226, v226, v248, vcc
	v_max_f32_e32 v5, v0, v0
	v_max_f32_e32 v6, v1, v1
	v_max_f32_e32 v5, v6, v5
	v_max3_f32 v5, v5, v7, v3
	v_max3_f32 v5, v5, v9, v8
	v_max3_f32 v5, v5, v12, v11
	v_max3_f32 v5, v5, v15, v14
	v_max3_f32 v5, v5, v213, v13
	v_max3_f32 v5, v5, v209, v205
	v_max3_f32 v6, v5, v227, v226
	ds_bpermute_b32 v48, v224, v6
	v_mov_b64_e32 v[78:79], v[46:47]
	v_mov_b32_e32 v5, v201
	v_mov_b32_e32 v10, v4
	v_mov_b64_e32 v[76:77], v[44:45]
	s_waitcnt lgkmcnt(0)
	v_max3_f32 v6, v4, v6, v48
	v_mov_b64_e32 v[62:63], v[30:31]
	v_mov_b64_e32 v[74:75], v[42:43]
	v_mov_b64_e32 v[72:73], v[40:41]
	v_mov_b64_e32 v[70:71], v[38:39]
	v_mov_b64_e32 v[68:69], v[36:37]
	v_mov_b64_e32 v[66:67], v[34:35]
	v_mov_b64_e32 v[64:65], v[32:33]
	v_cmp_gt_f32_e32 vcc, v6, v4
	v_mov_b64_e32 v[60:61], v[28:29]
	v_mov_b64_e32 v[58:59], v[26:27]
	v_mov_b64_e32 v[56:57], v[24:25]
	v_mov_b64_e32 v[54:55], v[22:23]
	v_mov_b64_e32 v[52:53], v[20:21]
	v_mov_b64_e32 v[50:51], v[18:19]
	v_mov_b64_e32 v[48:49], v[16:17]
	s_cbranch_vccz .LBB0_1049
	v_sub_f32_e32 v5, v4, v6
	v_exp_f32_e32 v10, v5
	s_nop 0
	v_mul_f32_e32 v5, v201, v10
	v_pk_mul_f32 v[62:63], v[30:31], v[10:11] op_sel_hi:[1,0]
	v_pk_mul_f32 v[60:61], v[28:29], v[10:11] op_sel_hi:[1,0]
	v_pk_mul_f32 v[58:59], v[26:27], v[10:11] op_sel_hi:[1,0]
	v_pk_mul_f32 v[56:57], v[24:25], v[10:11] op_sel_hi:[1,0]
	v_pk_mul_f32 v[54:55], v[22:23], v[10:11] op_sel_hi:[1,0]
	v_pk_mul_f32 v[52:53], v[20:21], v[10:11] op_sel_hi:[1,0]
	v_pk_mul_f32 v[50:51], v[18:19], v[10:11] op_sel_hi:[1,0]
	v_pk_mul_f32 v[48:49], v[16:17], v[10:11] op_sel_hi:[1,0]
	v_pk_mul_f32 v[78:79], v[46:47], v[10:11] op_sel_hi:[1,0]
	v_pk_mul_f32 v[76:77], v[44:45], v[10:11] op_sel_hi:[1,0]
	v_pk_mul_f32 v[74:75], v[42:43], v[10:11] op_sel_hi:[1,0]
	v_pk_mul_f32 v[72:73], v[40:41], v[10:11] op_sel_hi:[1,0]
	v_pk_mul_f32 v[70:71], v[38:39], v[10:11] op_sel_hi:[1,0]
	v_pk_mul_f32 v[68:69], v[36:37], v[10:11] op_sel_hi:[1,0]
	v_pk_mul_f32 v[66:67], v[34:35], v[10:11] op_sel_hi:[1,0]
	v_pk_mul_f32 v[64:65], v[32:33], v[10:11] op_sel_hi:[1,0]
	v_mov_b32_e32 v10, v6
